# GEMM: first K-loop iteration peeled with C=0 on first-touch MFMAs (no accumulator zeroing); workspace pointer from spilled lanes instead of a kernarg load per tile
# baseline (speedup 1.0000x reference)
; #define PG8_STAGE(bufoff, gbase, voff) do { _Pragma("unroll") for (int _i = 0; _i < 2; ++_i) \
;         __builtin_amdgcn_global_load_lds((const unsigned*)((const char*)(gbase) + (voff)[_i]), (PG8_LAS unsigned*)(lds + (bufoff) + ldsw + _i * 8192), 16, 0, 0); } while (0)
; #define PG8_LDA(dst, b, h) do { _Pragma("unroll") for (int m = 0; m < 4; ++m) _Pragma("unroll") for (int k = 0; k < 2; ++k) dst[m][k] = *(const PG8_LAS bf16x8*)(lds + PG8_SA(b, h) + aoff + m * 2048 + k * 1024); } while (0)
; #define PG8_LDB(dst, b, h) do { _Pragma("unroll") for (int n = 0; n < 2; ++n) _Pragma("unroll") for (int k = 0; k < 2; ++k) dst[n][k] = *(const PG8_LAS bf16x8*)(lds + PG8_SB(b, h) + boff + n * 2048 + k * 1024); } while (0)
; #define PG8_MMA(ai, bj, At, Bt) do { __builtin_amdgcn_s_setprio(1); _Pragma("unroll") for (int m = 0; m < 4; ++m) _Pragma("unroll") for (int n = 0; n < 2; ++n) _Pragma("unroll") for (int k = 0; k < 2; ++k) \
;         acc[ai][bj][m][n] = __builtin_amdgcn_mfma_f32_16x16x32_bf16(Bt[n][k], At[m][k], acc[ai][bj][m][n], 0, 0, 0); __builtin_amdgcn_s_setprio(0); } while (0)
; #define PG8_WAIT_V(n) asm volatile("s_waitcnt vmcnt(" #n ")" ::: "memory")
; #define PG8_WAIT_L(n) asm volatile("s_waitcnt lgkmcnt(" #n ")" ::: "memory")
; #define PG8_BAR __builtin_amdgcn_s_barrier()
; #define PG8_SCHED __builtin_amdgcn_sched_barrier(0)
; template <class Epi, class Sched, bool ALIGN_EPI = false, bool SP2 = false>
; __device__ __forceinline__ void gemm_phase(PG8_LAS unsigned char* lds, const Gemm g, const Sched& S, const Epi& E) {
;     ...
;     f32x4 acc[2][2][4][2];
; #pragma unroll
;     for (int a = 0; a < 2; ++a)
; #pragma unroll
;         for (int b = 0; b < 2; ++b)
; #pragma unroll
;             for (int m = 0; m < 4; ++m)
; #pragma unroll
;                 for (int n = 0; n < 2; ++n) acc[a][b][m][n] = (f32x4){0.f, 0.f, 0.f, 0.f};
;     ...
;             PG8_LDB(B0, 0, 0); PG8_LDB(B1, 0, 1); PG8_SCHED; PG8_LDA(At, 0, 0); PG8_STAGE(PG8_SA(1, 1), a1 + hstep, voffA);
;             PG8_WAIT_V(8); PG8_WAIT_L(0); PG8_BAR; PG8_MMA(0, 0, At, B0); PG8_MMA(0, 1, At, B1); PG8_BAR; PG8_SCHED;
;             PG8_LDA(At, 0, 1); PG8_STAGE(PG8_SB(0, 0), b2, voffB); PG8_STAGE(PG8_SB(0, 1), b2 + hstep, voffB); PG8_STAGE(PG8_SA(0, 0), a2, voffA);
;             PG8_WAIT_V(8); PG8_WAIT_L(0); PG8_BAR; PG8_MMA(1, 0, At, B0); PG8_MMA(1, 1, At, B1); PG8_BAR; PG8_SCHED;
.LBB0_58:
	s_add_u32 s4, s38, 0x80
	s_addc_u32 s5, s39, 0
	s_add_u32 s20, s34, 0x100
	s_addc_u32 s38, s35, 0
	s_mov_b32 s34, 0
	s_waitcnt vmcnt(0)
	s_add_i32 s39, s34, 2
	s_add_u32 s46, s4, 0x80
	s_addc_u32 s35, s5, 0
	s_add_i32 s48, 0, 0x10000
	s_cmp_eq_u32 s67, s34
	s_cselect_b32 s35, s27, s35
	s_cselect_b32 s34, s26, s46
	s_cselect_b32 s47, s29, s38
	s_cselect_b32 s46, s28, s20
	s_add_i32 s49, 0, 0x14000
	v_add_u32_e32 v142, s48, v227
	v_add_u32_e32 v158, s49, v227
	ds_read_b128 v[130:133], v142
	ds_read_b128 v[134:137], v142 offset:1024
	ds_read_b128 v[138:141], v142 offset:2048
	ds_read_b128 v[142:145], v142 offset:3072
	ds_read_b128 v[146:149], v158
	ds_read_b128 v[150:153], v158 offset:1024
	ds_read_b128 v[154:157], v158 offset:2048
	ds_read_b128 v[158:161], v158 offset:3072
	v_lshl_add_u64 v[208:209], s[4:5], 0, v[180:181]
	s_add_i32 m0, s58, 0xc000
	ds_read_b128 v[162:165], v229
	ds_read_b128 v[166:169], v229 offset:1024
	ds_read_b128 v[184:187], v229 offset:2048
	ds_read_b128 v[188:191], v229 offset:3072
	ds_read_b128 v[192:195], v229 offset:4096
	ds_read_b128 v[196:199], v229 offset:5120
	ds_read_b128 v[200:203], v229 offset:6144
	ds_read_b128 v[204:207], v229 offset:7168
	global_load_lds_dwordx4 v[208:209], off
	v_lshl_add_u64 v[208:209], s[4:5], 0, v[182:183]
	s_add_i32 m0, s58, 0xe000
	s_nop 0
	global_load_lds_dwordx4 v[208:209], off
	s_waitcnt vmcnt(8)
	s_waitcnt lgkmcnt(0)
	s_barrier
	s_setprio 1
	s_waitcnt lgkmcnt(0)
	v_mfma_f32_16x16x32_bf16 v[126:129], v[130:133], v[162:165], 0
	v_mfma_f32_16x16x32_bf16 v[122:125], v[138:141], v[162:165], 0
	v_mfma_f32_16x16x32_bf16 v[110:113], v[130:133], v[184:187], 0
	v_mfma_f32_16x16x32_bf16 v[106:109], v[138:141], v[184:187], 0
	v_mfma_f32_16x16x32_bf16 v[94:97], v[130:133], v[192:195], 0
	v_mfma_f32_16x16x32_bf16 v[90:93], v[138:141], v[192:195], 0
	v_mfma_f32_16x16x32_bf16 v[78:81], v[130:133], v[200:203], 0
	v_mfma_f32_16x16x32_bf16 v[74:77], v[138:141], v[200:203], 0
	v_mfma_f32_16x16x32_bf16 v[126:129], v[134:137], v[166:169], v[126:129]
	v_mfma_f32_16x16x32_bf16 v[122:125], v[142:145], v[166:169], v[122:125]
	v_mfma_f32_16x16x32_bf16 v[110:113], v[134:137], v[188:191], v[110:113]
	v_mfma_f32_16x16x32_bf16 v[106:109], v[142:145], v[188:191], v[106:109]
	v_mfma_f32_16x16x32_bf16 v[94:97], v[134:137], v[196:199], v[94:97]
	v_mfma_f32_16x16x32_bf16 v[90:93], v[142:145], v[196:199], v[90:93]
	v_mfma_f32_16x16x32_bf16 v[78:81], v[134:137], v[204:207], v[78:81]
	v_mfma_f32_16x16x32_bf16 v[74:77], v[142:145], v[204:207], v[74:77]
	s_setprio 0
	s_setprio 1
	v_mfma_f32_16x16x32_bf16 v[118:121], v[146:149], v[162:165], 0
	v_mfma_f32_16x16x32_bf16 v[114:117], v[154:157], v[162:165], 0
	v_mfma_f32_16x16x32_bf16 v[102:105], v[146:149], v[184:187], 0
	v_mfma_f32_16x16x32_bf16 v[98:101], v[154:157], v[184:187], 0
	v_mfma_f32_16x16x32_bf16 v[86:89], v[146:149], v[192:195], 0
	v_mfma_f32_16x16x32_bf16 v[82:85], v[154:157], v[192:195], 0
	v_mfma_f32_16x16x32_bf16 v[70:73], v[146:149], v[200:203], 0
	v_mfma_f32_16x16x32_bf16 v[66:69], v[154:157], v[200:203], 0
	v_mfma_f32_16x16x32_bf16 v[118:121], v[150:153], v[166:169], v[118:121]
	v_mfma_f32_16x16x32_bf16 v[114:117], v[158:161], v[166:169], v[114:117]
	v_mfma_f32_16x16x32_bf16 v[102:105], v[150:153], v[188:191], v[102:105]
	v_mfma_f32_16x16x32_bf16 v[98:101], v[158:161], v[188:191], v[98:101]
	v_mfma_f32_16x16x32_bf16 v[86:89], v[150:153], v[196:199], v[86:89]
	v_mfma_f32_16x16x32_bf16 v[82:85], v[158:161], v[196:199], v[82:85]
	v_mfma_f32_16x16x32_bf16 v[70:73], v[150:153], v[204:207], v[70:73]
	v_mfma_f32_16x16x32_bf16 v[66:69], v[158:161], v[204:207], v[66:69]
	s_setprio 0
	s_barrier
	s_add_i32 s48, s48, s57
	v_lshl_add_u64 v[208:209], s[46:47], 0, v[172:173]
	s_mov_b32 m0, s48
	ds_read_b128 v[162:165], v229 offset:16384
	ds_read_b128 v[166:169], v229 offset:17408
	ds_read_b128 v[184:187], v229 offset:18432
	ds_read_b128 v[188:191], v229 offset:19456
	ds_read_b128 v[192:195], v229 offset:20480
	ds_read_b128 v[196:199], v229 offset:21504
	ds_read_b128 v[200:203], v229 offset:22528
	ds_read_b128 v[204:207], v229 offset:23552
	global_load_lds_dwordx4 v[208:209], off
	s_add_i32 m0, s48, 0x2000
	v_lshl_add_u64 v[210:211], s[46:47], 0, v[176:177]
	s_add_u32 s46, s46, s16
	s_addc_u32 s47, s47, 0
	s_add_i32 s48, s49, s57
	global_load_lds_dwordx4 v[210:211], off
	v_lshl_add_u64 v[212:213], s[46:47], 0, v[172:173]
	s_mov_b32 m0, s48
	v_lshl_add_u64 v[214:215], s[46:47], 0, v[176:177]
	global_load_lds_dwordx4 v[212:213], off
	s_add_i32 m0, s48, 0x2000
	v_lshl_add_u64 v[230:231], s[34:35], 0, v[170:171]
	global_load_lds_dwordx4 v[214:215], off
	s_mov_b32 m0, s58
	v_lshl_add_u64 v[232:233], s[34:35], 0, v[174:175]
	global_load_lds_dwordx4 v[230:231], off
	s_mov_b32 m0, s59
	s_nop 0
	global_load_lds_dwordx4 v[232:233], off
	s_waitcnt vmcnt(8)
	s_waitcnt lgkmcnt(0)
	s_barrier
; #define PG8_STAGE(bufoff, gbase, voff) do { _Pragma("unroll") for (int _i = 0; _i < 2; ++_i) \
;         __builtin_amdgcn_global_load_lds((const unsigned*)((const char*)(gbase) + (voff)[_i]), (PG8_LAS unsigned*)(lds + (bufoff) + ldsw + _i * 8192), 16, 0, 0); } while (0)
; #define PG8_LDA(dst, b, h) do { _Pragma("unroll") for (int m = 0; m < 4; ++m) _Pragma("unroll") for (int k = 0; k < 2; ++k) dst[m][k] = *(const PG8_LAS bf16x8*)(lds + PG8_SA(b, h) + aoff + m * 2048 + k * 1024); } while (0)
; #define PG8_LDB(dst, b, h) do { _Pragma("unroll") for (int n = 0; n < 2; ++n) _Pragma("unroll") for (int k = 0; k < 2; ++k) dst[n][k] = *(const PG8_LAS bf16x8*)(lds + PG8_SB(b, h) + boff + n * 2048 + k * 1024); } while (0)
; #define PG8_MMA(ai, bj, At, Bt) do { __builtin_amdgcn_s_setprio(1); _Pragma("unroll") for (int m = 0; m < 4; ++m) _Pragma("unroll") for (int n = 0; n < 2; ++n) _Pragma("unroll") for (int k = 0; k < 2; ++k) \
;         acc[ai][bj][m][n] = __builtin_amdgcn_mfma_f32_16x16x32_bf16(Bt[n][k], At[m][k], acc[ai][bj][m][n], 0, 0, 0); __builtin_amdgcn_s_setprio(0); } while (0)
; #define PG8_WAIT_V(n) asm volatile("s_waitcnt vmcnt(" #n ")" ::: "memory")
; #define PG8_WAIT_L(n) asm volatile("s_waitcnt lgkmcnt(" #n ")" ::: "memory")
; #define PG8_BAR __builtin_amdgcn_s_barrier()
; #define PG8_SCHED __builtin_amdgcn_sched_barrier(0)
; template <class Epi, class Sched, bool ALIGN_EPI = false, bool SP2 = false>
; __device__ __forceinline__ void gemm_phase(PG8_LAS unsigned char* lds, const Gemm g, const Sched& S, const Epi& E) {
;     ...
;             PG8_WAIT_V(8); PG8_WAIT_L(0); PG8_BAR; PG8_MMA(1, 0, At, B0); PG8_MMA(1, 1, At, B1); PG8_BAR; PG8_SCHED;
;             PG8_LDB(B0, 1, 0); PG8_LDB(B1, 1, 1); PG8_SCHED; PG8_LDA(At, 1, 0); PG8_STAGE(PG8_SA(0, 1), a2 + hstep, voffA);
;             PG8_WAIT_V(8); PG8_WAIT_L(0); PG8_BAR; PG8_MMA(0, 0, At, B0); PG8_MMA(0, 1, At, B1); PG8_BAR; PG8_SCHED;
	s_setprio 1
	s_waitcnt lgkmcnt(0)
	v_mfma_f32_16x16x32_bf16 v[62:65], v[130:133], v[162:165], 0
	v_mfma_f32_16x16x32_bf16 v[58:61], v[138:141], v[162:165], 0
	v_mfma_f32_16x16x32_bf16 v[46:49], v[130:133], v[184:187], 0
	v_mfma_f32_16x16x32_bf16 v[42:45], v[138:141], v[184:187], 0
	v_mfma_f32_16x16x32_bf16 v[30:33], v[130:133], v[192:195], 0
	v_mfma_f32_16x16x32_bf16 v[26:29], v[138:141], v[192:195], 0
	v_mfma_f32_16x16x32_bf16 v[14:17], v[130:133], v[200:203], 0
	v_mfma_f32_16x16x32_bf16 v[10:13], v[138:141], v[200:203], 0
	v_mfma_f32_16x16x32_bf16 v[62:65], v[134:137], v[166:169], v[62:65]
	v_mfma_f32_16x16x32_bf16 v[58:61], v[142:145], v[166:169], v[58:61]
	v_mfma_f32_16x16x32_bf16 v[46:49], v[134:137], v[188:191], v[46:49]
	v_mfma_f32_16x16x32_bf16 v[42:45], v[142:145], v[188:191], v[42:45]
	v_mfma_f32_16x16x32_bf16 v[30:33], v[134:137], v[196:199], v[30:33]
	v_mfma_f32_16x16x32_bf16 v[26:29], v[142:145], v[196:199], v[26:29]
	v_mfma_f32_16x16x32_bf16 v[14:17], v[134:137], v[204:207], v[14:17]
	v_mfma_f32_16x16x32_bf16 v[10:13], v[142:145], v[204:207], v[10:13]
	s_setprio 0
	s_setprio 1
	v_mfma_f32_16x16x32_bf16 v[54:57], v[146:149], v[162:165], 0
	v_mfma_f32_16x16x32_bf16 v[50:53], v[154:157], v[162:165], 0
	v_mfma_f32_16x16x32_bf16 v[38:41], v[146:149], v[184:187], 0
	v_mfma_f32_16x16x32_bf16 v[34:37], v[154:157], v[184:187], 0
	v_mfma_f32_16x16x32_bf16 v[22:25], v[146:149], v[192:195], 0
	v_mfma_f32_16x16x32_bf16 v[18:21], v[154:157], v[192:195], 0
	v_mfma_f32_16x16x32_bf16 v[6:9], v[146:149], v[200:203], 0
	v_mfma_f32_16x16x32_bf16 v[2:5], v[154:157], v[200:203], 0
	v_mfma_f32_16x16x32_bf16 v[54:57], v[150:153], v[166:169], v[54:57]
	v_mfma_f32_16x16x32_bf16 v[50:53], v[158:161], v[166:169], v[50:53]
	v_mfma_f32_16x16x32_bf16 v[38:41], v[150:153], v[188:191], v[38:41]
	v_mfma_f32_16x16x32_bf16 v[34:37], v[158:161], v[188:191], v[34:37]
	v_mfma_f32_16x16x32_bf16 v[22:25], v[150:153], v[196:199], v[22:25]
	v_mfma_f32_16x16x32_bf16 v[18:21], v[158:161], v[196:199], v[18:21]
	v_mfma_f32_16x16x32_bf16 v[6:9], v[150:153], v[204:207], v[6:9]
	v_mfma_f32_16x16x32_bf16 v[2:5], v[158:161], v[204:207], v[2:5]
	s_setprio 0
	s_barrier
	s_add_i32 s46, 0, 0x18000
	s_add_i32 s47, 0, 0x1c000
	v_add_u32_e32 v142, s46, v227
	v_add_u32_e32 v158, s47, v227
	ds_read_b128 v[130:133], v142
	ds_read_b128 v[134:137], v142 offset:1024
	ds_read_b128 v[138:141], v142 offset:2048
	ds_read_b128 v[142:145], v142 offset:3072
	ds_read_b128 v[146:149], v158
	ds_read_b128 v[150:153], v158 offset:1024
	ds_read_b128 v[154:157], v158 offset:2048
	ds_read_b128 v[158:161], v158 offset:3072
	s_add_u32 s34, s34, s16
	s_addc_u32 s35, s35, 0
	s_mov_b32 m0, s60
	v_lshl_add_u64 v[234:235], s[34:35], 0, v[170:171]
	ds_read_b128 v[162:165], v229 offset:32768
	ds_read_b128 v[166:169], v229 offset:33792
	ds_read_b128 v[184:187], v229 offset:34816
	ds_read_b128 v[188:191], v229 offset:35840
	ds_read_b128 v[192:195], v229 offset:36864
	ds_read_b128 v[196:199], v229 offset:37888
	ds_read_b128 v[200:203], v229 offset:38912
	ds_read_b128 v[204:207], v229 offset:39936
	global_load_lds_dwordx4 v[234:235], off
	v_lshl_add_u64 v[234:235], s[34:35], 0, v[174:175]
	s_mov_b32 m0, s61
	s_nop 0
	global_load_lds_dwordx4 v[234:235], off
	s_waitcnt vmcnt(8)
	s_waitcnt lgkmcnt(0)
	s_barrier
	s_setprio 1
	s_waitcnt lgkmcnt(0)
	v_mfma_f32_16x16x32_bf16 v[126:129], v[130:133], v[162:165], v[126:129]
	v_mfma_f32_16x16x32_bf16 v[122:125], v[138:141], v[162:165], v[122:125]
	v_mfma_f32_16x16x32_bf16 v[110:113], v[130:133], v[184:187], v[110:113]
	v_mfma_f32_16x16x32_bf16 v[106:109], v[138:141], v[184:187], v[106:109]
	v_mfma_f32_16x16x32_bf16 v[94:97], v[130:133], v[192:195], v[94:97]
	v_mfma_f32_16x16x32_bf16 v[90:93], v[138:141], v[192:195], v[90:93]
	v_mfma_f32_16x16x32_bf16 v[78:81], v[130:133], v[200:203], v[78:81]
	v_mfma_f32_16x16x32_bf16 v[74:77], v[138:141], v[200:203], v[74:77]
	v_mfma_f32_16x16x32_bf16 v[126:129], v[134:137], v[166:169], v[126:129]
	v_mfma_f32_16x16x32_bf16 v[122:125], v[142:145], v[166:169], v[122:125]
	v_mfma_f32_16x16x32_bf16 v[110:113], v[134:137], v[188:191], v[110:113]
	v_mfma_f32_16x16x32_bf16 v[106:109], v[142:145], v[188:191], v[106:109]
	v_mfma_f32_16x16x32_bf16 v[94:97], v[134:137], v[196:199], v[94:97]
	v_mfma_f32_16x16x32_bf16 v[90:93], v[142:145], v[196:199], v[90:93]
	v_mfma_f32_16x16x32_bf16 v[78:81], v[134:137], v[204:207], v[78:81]
	v_mfma_f32_16x16x32_bf16 v[74:77], v[142:145], v[204:207], v[74:77]
	s_setprio 0
	s_setprio 1
	v_mfma_f32_16x16x32_bf16 v[118:121], v[146:149], v[162:165], v[118:121]
	v_mfma_f32_16x16x32_bf16 v[114:117], v[154:157], v[162:165], v[114:117]
	v_mfma_f32_16x16x32_bf16 v[102:105], v[146:149], v[184:187], v[102:105]
	v_mfma_f32_16x16x32_bf16 v[98:101], v[154:157], v[184:187], v[98:101]
	v_mfma_f32_16x16x32_bf16 v[86:89], v[146:149], v[192:195], v[86:89]
	v_mfma_f32_16x16x32_bf16 v[82:85], v[154:157], v[192:195], v[82:85]
	v_mfma_f32_16x16x32_bf16 v[70:73], v[146:149], v[200:203], v[70:73]
	v_mfma_f32_16x16x32_bf16 v[66:69], v[154:157], v[200:203], v[66:69]
	v_mfma_f32_16x16x32_bf16 v[118:121], v[150:153], v[166:169], v[118:121]
	v_mfma_f32_16x16x32_bf16 v[114:117], v[158:161], v[166:169], v[114:117]
	v_mfma_f32_16x16x32_bf16 v[102:105], v[150:153], v[188:191], v[102:105]
	v_mfma_f32_16x16x32_bf16 v[98:101], v[158:161], v[188:191], v[98:101]
	v_mfma_f32_16x16x32_bf16 v[86:89], v[150:153], v[196:199], v[86:89]
	v_mfma_f32_16x16x32_bf16 v[82:85], v[158:161], v[196:199], v[82:85]
	v_mfma_f32_16x16x32_bf16 v[70:73], v[150:153], v[204:207], v[70:73]
	v_mfma_f32_16x16x32_bf16 v[66:69], v[158:161], v[204:207], v[66:69]
	s_setprio 0
	s_barrier
; #define PG8_STAGE(bufoff, gbase, voff) do { _Pragma("unroll") for (int _i = 0; _i < 2; ++_i) \
;         __builtin_amdgcn_global_load_lds((const unsigned*)((const char*)(gbase) + (voff)[_i]), (PG8_LAS unsigned*)(lds + (bufoff) + ldsw + _i * 8192), 16, 0, 0); } while (0)
; #define PG8_LDA(dst, b, h) do { _Pragma("unroll") for (int m = 0; m < 4; ++m) _Pragma("unroll") for (int k = 0; k < 2; ++k) dst[m][k] = *(const PG8_LAS bf16x8*)(lds + PG8_SA(b, h) + aoff + m * 2048 + k * 1024); } while (0)
; #define PG8_MMA(ai, bj, At, Bt) do { __builtin_amdgcn_s_setprio(1); _Pragma("unroll") for (int m = 0; m < 4; ++m) _Pragma("unroll") for (int n = 0; n < 2; ++n) _Pragma("unroll") for (int k = 0; k < 2; ++k) \
;         acc[ai][bj][m][n] = __builtin_amdgcn_mfma_f32_16x16x32_bf16(Bt[n][k], At[m][k], acc[ai][bj][m][n], 0, 0, 0); __builtin_amdgcn_s_setprio(0); } while (0)
; #define PG8_WAIT_V(n) asm volatile("s_waitcnt vmcnt(" #n ")" ::: "memory")
; #define PG8_WAIT_L(n) asm volatile("s_waitcnt lgkmcnt(" #n ")" ::: "memory")
; #define PG8_BAR __builtin_amdgcn_s_barrier()
; #define PG8_SCHED __builtin_amdgcn_sched_barrier(0)
; template <class Epi, class Sched, bool ALIGN_EPI = false, bool SP2 = false>
; __device__ __forceinline__ void gemm_phase(PG8_LAS unsigned char* lds, const Gemm g, const Sched& S, const Epi& E) {
;     ...
;             PG8_LDA(At, 1, 1); PG8_STAGE(PG8_SB(1, 0), b3, voffB); PG8_STAGE(PG8_SB(1, 1), b3 + hstep, voffB); PG8_STAGE(PG8_SA(1, 0), a3, voffA);
;             PG8_WAIT_V(8); PG8_WAIT_L(0); PG8_BAR; PG8_MMA(1, 0, At, B0); PG8_MMA(1, 1, At, B1); PG8_BAR; PG8_SCHED;
	s_add_i32 s34, s46, s57
	v_lshl_add_u64 v[208:209], v[208:209], 0, s[2:3]
	s_mov_b32 m0, s34
	ds_read_b128 v[162:165], v229 offset:49152
	ds_read_b128 v[166:169], v229 offset:50176
	ds_read_b128 v[184:187], v229 offset:51200
	ds_read_b128 v[188:191], v229 offset:52224
	ds_read_b128 v[192:195], v229 offset:53248
	ds_read_b128 v[196:199], v229 offset:54272
	ds_read_b128 v[200:203], v229 offset:55296
	ds_read_b128 v[204:207], v229 offset:56320
	global_load_lds_dwordx4 v[208:209], off
	v_lshl_add_u64 v[208:209], v[210:211], 0, s[2:3]
	s_add_i32 m0, s34, 0x2000
	s_add_i32 s34, s47, s57
	global_load_lds_dwordx4 v[208:209], off
	v_lshl_add_u64 v[208:209], v[212:213], 0, s[2:3]
	s_mov_b32 m0, s34
	s_nop 0
	global_load_lds_dwordx4 v[208:209], off
	v_lshl_add_u64 v[208:209], v[214:215], 0, s[2:3]
	s_add_i32 m0, s34, 0x2000
	s_nop 0
	global_load_lds_dwordx4 v[208:209], off
	v_lshl_add_u64 v[208:209], v[230:231], 0, s[2:3]
	s_mov_b32 m0, s62
	s_nop 0
	global_load_lds_dwordx4 v[208:209], off
	v_lshl_add_u64 v[208:209], v[232:233], 0, s[2:3]
	s_mov_b32 m0, s63
	s_nop 0
	global_load_lds_dwordx4 v[208:209], off
	s_waitcnt vmcnt(8)
	s_waitcnt lgkmcnt(0)
	s_barrier
	s_setprio 1
	s_waitcnt lgkmcnt(0)
	v_mfma_f32_16x16x32_bf16 v[62:65], v[130:133], v[162:165], v[62:65]
	v_mfma_f32_16x16x32_bf16 v[58:61], v[138:141], v[162:165], v[58:61]
	v_mfma_f32_16x16x32_bf16 v[46:49], v[130:133], v[184:187], v[46:49]
	v_mfma_f32_16x16x32_bf16 v[42:45], v[138:141], v[184:187], v[42:45]
	v_mfma_f32_16x16x32_bf16 v[30:33], v[130:133], v[192:195], v[30:33]
	v_mfma_f32_16x16x32_bf16 v[26:29], v[138:141], v[192:195], v[26:29]
	v_mfma_f32_16x16x32_bf16 v[14:17], v[130:133], v[200:203], v[14:17]
	v_mfma_f32_16x16x32_bf16 v[10:13], v[138:141], v[200:203], v[10:13]
	v_mfma_f32_16x16x32_bf16 v[62:65], v[134:137], v[166:169], v[62:65]
	v_mfma_f32_16x16x32_bf16 v[58:61], v[142:145], v[166:169], v[58:61]
	v_mfma_f32_16x16x32_bf16 v[46:49], v[134:137], v[188:191], v[46:49]
	v_mfma_f32_16x16x32_bf16 v[42:45], v[142:145], v[188:191], v[42:45]
	v_mfma_f32_16x16x32_bf16 v[30:33], v[134:137], v[196:199], v[30:33]
	v_mfma_f32_16x16x32_bf16 v[26:29], v[142:145], v[196:199], v[26:29]
	v_mfma_f32_16x16x32_bf16 v[14:17], v[134:137], v[204:207], v[14:17]
	v_mfma_f32_16x16x32_bf16 v[10:13], v[142:145], v[204:207], v[10:13]
	s_setprio 0
	s_setprio 1
	v_mfma_f32_16x16x32_bf16 v[54:57], v[146:149], v[162:165], v[54:57]
	v_mfma_f32_16x16x32_bf16 v[50:53], v[154:157], v[162:165], v[50:53]
	v_mfma_f32_16x16x32_bf16 v[38:41], v[146:149], v[184:187], v[38:41]
	v_mfma_f32_16x16x32_bf16 v[34:37], v[154:157], v[184:187], v[34:37]
	v_mfma_f32_16x16x32_bf16 v[22:25], v[146:149], v[192:195], v[22:25]
	v_mfma_f32_16x16x32_bf16 v[18:21], v[154:157], v[192:195], v[18:21]
	v_mfma_f32_16x16x32_bf16 v[6:9], v[146:149], v[200:203], v[6:9]
	v_mfma_f32_16x16x32_bf16 v[2:5], v[154:157], v[200:203], v[2:5]
	v_mfma_f32_16x16x32_bf16 v[54:57], v[150:153], v[166:169], v[54:57]
	v_mfma_f32_16x16x32_bf16 v[50:53], v[158:161], v[166:169], v[50:53]
	v_mfma_f32_16x16x32_bf16 v[38:41], v[150:153], v[188:191], v[38:41]
	v_mfma_f32_16x16x32_bf16 v[34:37], v[158:161], v[188:191], v[34:37]
	v_mfma_f32_16x16x32_bf16 v[22:25], v[150:153], v[196:199], v[22:25]
	v_mfma_f32_16x16x32_bf16 v[18:21], v[158:161], v[196:199], v[18:21]
	v_mfma_f32_16x16x32_bf16 v[6:9], v[150:153], v[204:207], v[6:9]
	v_mfma_f32_16x16x32_bf16 v[2:5], v[158:161], v[204:207], v[2:5]
	s_setprio 0
	s_barrier
	s_add_u32 s4, s4, 0x100
	s_addc_u32 s5, s5, 0
	s_add_u32 s20, s20, 0x100
	s_addc_u32 s38, s38, 0
	s_cmp_ge_u32 s39, s65
	s_mov_b32 s34, s39
	s_cbranch_scc1 .Lmy_k_exit

; #define PG8_BAR __builtin_amdgcn_s_barrier()
; template <class Epi, class Sched, bool ALIGN_EPI = false, bool SP2 = false>
; __device__ __forceinline__ void gemm_phase(PG8_LAS unsigned char* lds, const Gemm g, const Sched& S, const Epi& E) {
;     ...
;         if constexpr (ALIGN_EPI) { if (wr == 0) PG8_BAR; }
;         if constexpr (!Epi::AFTER_DRAIN) { E(acc, cur, wr, wc, fr, fq); S.done(cur); }
; __device__ __forceinline__ void epi_all_run(const void* Pk_, int l, int s, const f32x4 (&acc)[2][2][4][2], const pg8::Unit& u, int wr, int wc, int fr, int fq) {
;         CA* Pl = (CA*)Pk_; asm volatile("" : "+s"(Pl), "+s"(l), "+s"(s)); CA& A = *Pl;
;         unsigned char* const ws = A.ws;
;         const int row0 = u.pm * 256 + wr * 64 + fr; const int b = u.pm >> 4;
;         if (s == 0 || s == 5) {
.Lmy_k_exit:
	s_and_b64 vcc, exec, s[24:25]
	s_cbranch_vccz .LBB0_62
	s_barrier
.LBB0_62:
	v_readlane_b32 s4, v238, 2
	v_readlane_b32 s5, v238, 3
	s_mov_b32 s76, s37
	s_mov_b32 s75, s88
	v_readlane_b32 s34, v236, 1
	v_readlane_b32 s35, v236, 2
	s_cmp_lt_i32 s76, 2
	v_lshl_add_u32 v184, s31, 8, v1
	s_cbranch_scc1 .LBB0_65
	s_cmp_gt_i32 s76, 4
	s_cbranch_scc0 .LBB0_66
	s_cmp_lg_u32 s76, 5
	s_mov_b64 s[38:39], -1
	s_cselect_b64 s[46:47], -1, 0
	s_cbranch_execz .LBB0_67
	s_branch .LBB0_88
